# v41 + cross-phase rebalancing: 40 weight-conversion items per WG run at the end of P0 (all 8 waves idle there)
# speedup vs baseline: 1.0025x; 1.0008x over previous
_Z8skel_fwd4Args:
	s_mov_b32 s101, 0
	s_load_dword s92, s[0:1], 0xc0
	s_mov_b32 s87, s2
	s_add_u32 s2, s0, 0xc0
	s_addc_u32 s3, s1, 0
	v_readfirstlane_b32 s63, v0
	v_writelane_b32 v240, s2, 0
	s_mov_b32 s94, s87
	s_nop 0
	v_writelane_b32 v240, s3, 1
	s_waitcnt lgkmcnt(0)
	s_and_b32 s2, s92, 7
	s_cmp_lg_u32 s2, 0
	s_cbranch_scc1 .LBB0_2
	s_ashr_i32 s3, s87, 31
	s_lshr_b32 s3, s3, 29
	s_add_i32 s3, s87, s3
	s_and_b32 s4, s3, -8
	s_ashr_i32 s2, s92, 3
	s_sub_i32 s4, s87, s4
	s_mul_i32 s2, s2, s4
	s_ashr_i32 s3, s3, 3
	s_add_i32 s94, s2, s3

.LBB0_27:
	s_or_b64 exec, exec, s[0:1]
	v_readlane_b32 s93, v240, 15
	v_readlane_b32 s95, v240, 14
	s_mov_b32 s101, 1
	s_branch .LBB0_89
.Lp0_cont:
	s_cmp_lt_i32 s97, 2
	s_cbranch_scc1 .LBB0_77
	s_waitcnt vmcnt(0)
	v_cmp_eq_u32_e32 vcc, 0, v0
	s_waitcnt lgkmcnt(0)
	s_barrier
	s_and_saveexec_b64 s[0:1], vcc
	s_cbranch_execz .LBB0_76
	v_readlane_b32 s2, v240, 12
	s_waitcnt vmcnt(0) expcnt(0) lgkmcnt(0)
	s_nop 0
	v_mov_b32_e32 v1, s2
	ds_read_b32 v3, v1
	ds_read_b32 v1, v1 offset:4
	s_waitcnt lgkmcnt(1)
	v_cmp_ne_u32_e32 vcc, 0, v3
	s_cbranch_vccnz .LBB0_44
	v_readlane_b32 s2, v240, 0
	v_readlane_b32 s3, v240, 1
	s_load_dwordx2 s[6:7], s[2:3], 0x4
	s_add_u32 s2, s84, 0x4200
	s_addc_u32 s3, s85, 0
	s_add_u32 s4, s84, 0x4400
	s_addc_u32 s5, s85, 0
	s_waitcnt lgkmcnt(0)
	s_mul_i32 s33, s6, s92
	s_add_u32 s6, s84, 0x4500
	s_mul_i32 s33, s33, s7
	s_addc_u32 s7, s85, 0
	s_add_u32 s22, s84, 0x4600
	s_addc_u32 s23, s85, 0
	s_add_u32 s24, s84, 0x4700
	s_addc_u32 s25, s85, 0
	s_add_u32 s26, s84, 0x4800
	s_addc_u32 s27, s85, 0
	s_add_u32 s28, s84, 0x4900
	s_addc_u32 s29, s85, 0
	s_add_u32 s30, s84, 0x4a00
	s_addc_u32 s31, s85, 0
	s_add_u32 s34, s84, 0x4b00
	s_addc_u32 s35, s85, 0
	s_add_u32 s36, s84, 0x4c00
	s_addc_u32 s37, s85, 0
	s_add_u32 s38, s84, 0x4d00
	s_addc_u32 s39, s85, 0
	s_add_u32 s40, s84, 0x4e00
	s_addc_u32 s41, s85, 0
	s_add_u32 s42, s84, 0x4f00
	s_addc_u32 s43, s85, 0
	s_add_u32 s44, s84, 0x5000
	s_addc_u32 s45, s85, 0
	s_add_u32 s46, s84, 0x5100
	s_addc_u32 s47, s85, 0
	s_add_u32 s52, s84, 0x5200
	s_addc_u32 s53, s85, 0
	s_add_u32 s54, s84, 0x5300
	s_addc_u32 s55, s85, 0
	s_mov_b32 s62, 1
	v_mov_b32_e32 v17, 0
	s_branch .LBB0_32

.LBB0_89:
	v_lshlrev_b32_e32 v1, 2, v0
	s_cmpk_eq_i32 s92, 0x100
	s_movk_i32 s0, 0x7600
	v_and_b32_e32 v68, 28, v1
	s_cselect_b32 s4, s0, 0xa100
	s_cmp_eq_u32 s101, 1
	s_cselect_b32 s4, 0x2800, s4
	s_ashr_i32 s30, s94, 31
	s_ashr_i32 s31, s92, 31
	v_and_b32_e32 v66, 56, v0
	v_mov_b32_e32 v71, 0
	v_lshlrev_b32_e32 v70, 2, v68
	s_cmp_lg_u64 s[20:21], 0
	s_waitcnt lgkmcnt(0)
	v_lshl_add_u64 v[72:73], s[50:51], 0, v[70:71]
	v_lshlrev_b32_e32 v70, 1, v66
	s_mov_b32 s5, 0
	s_cselect_b64 s[2:3], -1, 0
	s_add_u32 s33, s84, 0x25400000
	v_lshl_add_u64 v[2:3], s[84:85], 0, v[70:71]
	s_mov_b64 s[6:7], 0x1000000
	v_cmp_eq_u32_e64 s[0:1], 0, v154
	s_addc_u32 s34, s85, 0
	v_lshl_add_u64 v[74:75], v[2:3], 0, s[6:7]
	s_add_i32 s35, 0, 0x20190
	v_mov_b64_e32 v[76:77], s[4:5]
	s_movk_i32 s36, 0x2b00
	s_movk_i32 s37, 0x5000
	s_mov_b32 s38, 0xa000
	s_mov_b32 s39, 0x10000
	s_mov_b32 s40, 0xac000
	s_mov_b32 s41, 0xb1000
	s_mov_b32 s42, 0xb6000
	s_mov_b64 s[4:5], 0xbc200
	s_mov_b32 s43, 0x15800
	s_movk_i32 s44, 0x1000
	s_mov_b64 s[6:7], 0x80
	s_mov_b32 s45, 0x11000
	s_mov_b64 s[12:13], 0x11800
	v_lshlrev_b32_e32 v70, 2, v68
	v_lshlrev_b32_e32 v78, 1, v66
	s_branch .LBB0_92

.LBB0_120:
	s_cmp_eq_u32 s101, 1
	s_cbranch_scc0 .Lp0_notcall
	s_mov_b32 s101, 0
	s_barrier
	v_mov_b32_e32 v1, 0x20190
	v_mov_b32_e32 v2, 40
	ds_write_b32 v1, v2
	v_readlane_b32 s2, v240, 0
	v_readlane_b32 s3, v240, 1
	s_nop 4
	s_load_dwordx4 s[12:15], s[2:3], -0xb0
	s_load_dwordx2 s[48:49], s[2:3], -0x50
	s_waitcnt lgkmcnt(0)
	s_barrier
	s_branch .Lp0_cont
